# FoX pair loop: packed f32 fma/add in the softmax (fewer vector instructions), v_permlane32_swap cross-half reductions
# speedup vs baseline: 1.0010x; 1.0010x over previous
.Lfox_entry:
	s_waitcnt vmcnt(0)
	v_lshlrev_b32_e32 v2, 2, v220
	v_add_u32_e32 v3, 0x10000, v2
	ds_write_b32 v2, v146 offset:0
	ds_write_b32 v2, v147 offset:2048
	ds_write_b32 v2, v148 offset:4096
	ds_write_b32 v2, v149 offset:6144
	ds_write_b32 v2, v150 offset:8192
	ds_write_b32 v2, v151 offset:10240
	ds_write_b32 v2, v152 offset:12288
	ds_write_b32 v2, v153 offset:14336
	ds_write_b32 v2, v154 offset:16384
	ds_write_b32 v2, v155 offset:18432
	ds_write_b32 v2, v156 offset:20480
	ds_write_b32 v2, v157 offset:22528
	ds_write_b32 v2, v158 offset:24576
	ds_write_b32 v2, v159 offset:26624
	ds_write_b32 v2, v160 offset:28672
	ds_write_b32 v2, v161 offset:30720
	ds_write_b32 v2, v162 offset:32768
	ds_write_b32 v2, v163 offset:34816
	ds_write_b32 v2, v164 offset:36864
	ds_write_b32 v2, v165 offset:38912
	ds_write_b32 v2, v166 offset:40960
	ds_write_b32 v2, v167 offset:43008
	ds_write_b32 v2, v168 offset:45056
	ds_write_b32 v2, v169 offset:47104
	ds_write_b32 v2, v170 offset:49152
	ds_write_b32 v2, v183 offset:51200
	ds_write_b32 v2, v184 offset:53248
	ds_write_b32 v2, v185 offset:55296
	ds_write_b32 v2, v186 offset:57344
	ds_write_b32 v2, v187 offset:59392
	ds_write_b32 v2, v188 offset:61440
	ds_write_b32 v2, v189 offset:63488
	ds_write_b32 v3, v190 offset:0
	ds_write_b32 v3, v191 offset:2048
	ds_write_b32 v3, v192 offset:4096
	ds_write_b32 v3, v193 offset:6144
	ds_write_b32 v3, v194 offset:8192
	ds_write_b32 v3, v195 offset:10240
	ds_write_b32 v3, v196 offset:12288
	ds_write_b32 v3, v197 offset:14336
	ds_write_b32 v3, v198 offset:16384
	ds_write_b32 v3, v199 offset:18432
	ds_write_b32 v3, v200 offset:20480
	ds_write_b32 v3, v201 offset:22528
	ds_write_b32 v3, v202 offset:24576
	ds_write_b32 v3, v203 offset:26624
	ds_write_b32 v3, v204 offset:28672
	ds_write_b32 v3, v205 offset:30720
	ds_write_b32 v3, v206 offset:32768
	ds_write_b32 v3, v207 offset:34816
	ds_write_b32 v3, v208 offset:36864
	ds_write_b32 v3, v209 offset:38912
	ds_write_b32 v3, v210 offset:40960
	ds_write_b32 v3, v211 offset:43008
	ds_write_b32 v3, v212 offset:45056
	ds_write_b32 v3, v213 offset:47104
	ds_write_b32 v3, v214 offset:49152
	ds_write_b32 v3, v215 offset:51200
	ds_write_b32 v3, v216 offset:53248
	v_lshrrev_b32_e32 v2, 6, v220
	v_lshlrev_b32_e32 v2, 8, v2
	v_add_u32_e32 v2, 0x1d800, v2
	v_mov_b32_e32 v3, s2
	ds_write_b32 v2, v3 offset:0
	v_mov_b32_e32 v3, s3
	ds_write_b32 v2, v3 offset:4
	v_mov_b32_e32 v3, s4
	ds_write_b32 v2, v3 offset:8
	v_mov_b32_e32 v3, s5
	ds_write_b32 v2, v3 offset:12
	v_mov_b32_e32 v3, s6
	ds_write_b32 v2, v3 offset:16
	v_mov_b32_e32 v3, s7
	ds_write_b32 v2, v3 offset:20
	v_mov_b32_e32 v3, s8
	ds_write_b32 v2, v3 offset:24
	v_mov_b32_e32 v3, s9
	ds_write_b32 v2, v3 offset:28
	v_mov_b32_e32 v3, s10
	ds_write_b32 v2, v3 offset:32
	v_mov_b32_e32 v3, s11
	ds_write_b32 v2, v3 offset:36
	v_mov_b32_e32 v3, s12
	ds_write_b32 v2, v3 offset:40
	v_mov_b32_e32 v3, s13
	ds_write_b32 v2, v3 offset:44
	v_mov_b32_e32 v3, s14
	ds_write_b32 v2, v3 offset:48
	v_mov_b32_e32 v3, s15
	ds_write_b32 v2, v3 offset:52
	v_mov_b32_e32 v3, s16
	ds_write_b32 v2, v3 offset:56
	v_mov_b32_e32 v3, s17
	ds_write_b32 v2, v3 offset:60
	v_mov_b32_e32 v3, s18
	ds_write_b32 v2, v3 offset:64
	v_mov_b32_e32 v3, s19
	ds_write_b32 v2, v3 offset:68
	v_mov_b32_e32 v3, s20
	ds_write_b32 v2, v3 offset:72
	v_mov_b32_e32 v3, s21
	ds_write_b32 v2, v3 offset:76
	v_mov_b32_e32 v3, s22
	ds_write_b32 v2, v3 offset:80
	v_mov_b32_e32 v3, s23
	ds_write_b32 v2, v3 offset:84
	v_mov_b32_e32 v3, s24
	ds_write_b32 v2, v3 offset:88
	v_mov_b32_e32 v3, s25
	ds_write_b32 v2, v3 offset:92
	v_mov_b32_e32 v3, s26
	ds_write_b32 v2, v3 offset:96
	v_mov_b32_e32 v3, s27
	ds_write_b32 v2, v3 offset:100
	v_mov_b32_e32 v3, s28
	ds_write_b32 v2, v3 offset:104
	v_mov_b32_e32 v3, s29
	ds_write_b32 v2, v3 offset:108
	v_mov_b32_e32 v3, s30
	ds_write_b32 v2, v3 offset:112
	v_mov_b32_e32 v3, s31
	ds_write_b32 v2, v3 offset:116
	v_mov_b32_e32 v3, s34
	ds_write_b32 v2, v3 offset:120
	v_mov_b32_e32 v3, s35
	ds_write_b32 v2, v3 offset:124
	v_mov_b32_e32 v3, s36
	ds_write_b32 v2, v3 offset:128
	v_mov_b32_e32 v3, s37
	ds_write_b32 v2, v3 offset:132
	v_mov_b32_e32 v3, s38
	ds_write_b32 v2, v3 offset:136
	v_mov_b32_e32 v3, s39
	ds_write_b32 v2, v3 offset:140
	v_mov_b32_e32 v3, s40
	ds_write_b32 v2, v3 offset:144
	v_mov_b32_e32 v3, s41
	ds_write_b32 v2, v3 offset:148
	v_mov_b32_e32 v3, s42
	ds_write_b32 v2, v3 offset:152
	v_mov_b32_e32 v3, s43
	ds_write_b32 v2, v3 offset:156
	v_mov_b32_e32 v3, s44
	ds_write_b32 v2, v3 offset:160
	v_mov_b32_e32 v3, s45
	ds_write_b32 v2, v3 offset:164
	s_load_dwordx2 s[20:21], s[70:71], 0x98
	v_readlane_b32 s22, v254, 0
	v_and_b32_e32 v195, 31, v173
	v_lshrrev_b32_e32 v196, 5, v173
	v_lshlrev_b32_e32 v194, 4, v173
	v_lshlrev_b32_e32 v190, 4, v195
	v_mov_b32_e32 v193, 0xff800000
	v_lshlrev_b32_e32 v183, 2, v196
	v_sub_u32_e32 v170, v195, v183
	s_mov_b32 s14, 0x3e38aa3b
	v_mov_b32_e32 v192, 0x3e38aa3b
	s_mov_b32 s44, -1
	s_mov_b32 s45, 0
	v_cmp_eq_u32_e32 vcc, 0, v196
	v_mov_b32_e32 v183, 0x3f803f80
	v_mov_b32_e32 v184, 0x3f80
	s_nop 0
	v_cndmask_b32_e32 v70, 0, v183, vcc
	v_cndmask_b32_e32 v71, 0, v184, vcc
	v_mov_b32_e32 v72, 0
	v_mov_b32_e32 v73, 0
	v_mov_b32_e32 v18, 0
	v_mov_b32_e32 v19, 0
	v_mov_b32_e32 v20, 0
	v_mov_b32_e32 v21, 0
	s_waitcnt lgkmcnt(0)

.Lfox_loop:
	s_waitcnt vmcnt(4)
	v_mfma_f32_32x32x16_bf16 v[138:153], v[2:5], v[38:41], 0
	v_mfma_f32_32x32x16_bf16 v[138:153], v[6:9], v[42:45], v[138:153]
	v_mfma_f32_32x32x16_bf16 v[138:153], v[10:13], v[46:49], v[138:153]
	v_mfma_f32_32x32x16_bf16 v[138:153], v[14:17], v[50:53], v[138:153]
	v_mfma_f32_32x32x16_bf16 v[138:153], v[18:21], v[70:73], v[138:153]
	v_mfma_f32_32x32x16_bf16 v[154:169], v[2:5], v[54:57], 0
	s_nop 7
	s_nop 4
	v_max3_f32 v183, v138, v139, v140
	v_max3_f32 v184, v141, v142, v143
	v_max3_f32 v185, v144, v145, v146
	v_max3_f32 v186, v147, v148, v149
	v_max3_f32 v187, v150, v151, v152
	v_max3_f32 v183, v183, v184, v185
	v_max3_f32 v186, v186, v187, v153
	v_max_f32_e32 v183, v183, v186
	v_mov_b32_e32 v184, v183
	s_nop 1
	v_permlane32_swap_b32_e32 v184, v183
	v_max_f32_e32 v183, v183, v184
	v_fma_f32 v183, v183, s14, v199
	v_max_f32_e32 v184, v197, v183
	v_mfma_f32_32x32x16_bf16 v[154:169], v[6:9], v[58:61], v[154:169]
	v_sub_f32_e32 v186, v197, v184
	v_exp_f32_e32 v186, v186
	v_mov_b32_e32 v197, v184
	v_sub_f32_e32 v200, v199, v184
	v_pk_fma_f32 v[138:139], v[138:139], v[192:193], v[200:201] op_sel_hi:[1,0,0]
	v_exp_f32_e32 v138, v138
	v_exp_f32_e32 v139, v139
	v_pk_fma_f32 v[140:141], v[140:141], v[192:193], v[200:201] op_sel_hi:[1,0,0]
	v_exp_f32_e32 v140, v140
	v_exp_f32_e32 v141, v141
	v_pk_fma_f32 v[142:143], v[142:143], v[192:193], v[200:201] op_sel_hi:[1,0,0]
	v_exp_f32_e32 v142, v142
	v_exp_f32_e32 v143, v143
	v_pk_fma_f32 v[144:145], v[144:145], v[192:193], v[200:201] op_sel_hi:[1,0,0]
	v_mfma_f32_32x32x16_bf16 v[154:169], v[10:13], v[62:65], v[154:169]
	v_exp_f32_e32 v144, v144
	v_exp_f32_e32 v145, v145
	v_pk_fma_f32 v[146:147], v[146:147], v[192:193], v[200:201] op_sel_hi:[1,0,0]
	v_exp_f32_e32 v146, v146
	v_exp_f32_e32 v147, v147
	v_pk_fma_f32 v[148:149], v[148:149], v[192:193], v[200:201] op_sel_hi:[1,0,0]
	v_exp_f32_e32 v148, v148
	v_exp_f32_e32 v149, v149
	v_pk_fma_f32 v[150:151], v[150:151], v[192:193], v[200:201] op_sel_hi:[1,0,0]
	v_exp_f32_e32 v150, v150
	v_exp_f32_e32 v151, v151
	v_pk_fma_f32 v[152:153], v[152:153], v[192:193], v[200:201] op_sel_hi:[1,0,0]
	v_exp_f32_e32 v152, v152
	v_exp_f32_e32 v153, v153
	v_mfma_f32_32x32x16_bf16 v[154:169], v[14:17], v[66:69], v[154:169]
	v_mul_f32_e32 v198, v198, v186
	v_pk_mul_f32 v[74:75], v[74:75], v[186:187] op_sel_hi:[1,0]
	v_pk_mul_f32 v[76:77], v[76:77], v[186:187] op_sel_hi:[1,0]
	v_pk_mul_f32 v[78:79], v[78:79], v[186:187] op_sel_hi:[1,0]
	v_pk_mul_f32 v[80:81], v[80:81], v[186:187] op_sel_hi:[1,0]
	v_pk_mul_f32 v[82:83], v[82:83], v[186:187] op_sel_hi:[1,0]
	v_pk_mul_f32 v[84:85], v[84:85], v[186:187] op_sel_hi:[1,0]
	v_pk_mul_f32 v[86:87], v[86:87], v[186:187] op_sel_hi:[1,0]
	v_pk_mul_f32 v[88:89], v[88:89], v[186:187] op_sel_hi:[1,0]
	v_pk_mul_f32 v[90:91], v[90:91], v[186:187] op_sel_hi:[1,0]
	v_pk_mul_f32 v[92:93], v[92:93], v[186:187] op_sel_hi:[1,0]
	v_pk_mul_f32 v[94:95], v[94:95], v[186:187] op_sel_hi:[1,0]
	v_pk_mul_f32 v[96:97], v[96:97], v[186:187] op_sel_hi:[1,0]
	v_pk_mul_f32 v[98:99], v[98:99], v[186:187] op_sel_hi:[1,0]
	v_mfma_f32_32x32x16_bf16 v[154:169], v[18:21], v[70:73], v[154:169]
	s_add_i32 s18, s16, 1
	s_lshl_b32 s17, s18, 12
	v_add_u32_e32 v207, s17, v194
	global_load_dwordx4 v[2:5], v207, s[4:5]
	global_load_dwordx4 v[6:9], v207, s[4:5] offset:1024
	global_load_dwordx4 v[10:13], v207, s[4:5] offset:2048
	global_load_dwordx4 v[14:17], v207, s[4:5] offset:3072
	s_lshl_b32 s17, s18, 9
	v_add_u32_e32 v209, s17, v190
	s_mov_b64 exec, s[44:45]
	global_load_dwordx4 v[18:21], v209, s[8:9]
	s_mov_b64 exec, -1
	v_pk_mul_f32 v[100:101], v[100:101], v[186:187] op_sel_hi:[1,0]
	v_pk_mul_f32 v[102:103], v[102:103], v[186:187] op_sel_hi:[1,0]
	v_pk_mul_f32 v[104:105], v[104:105], v[186:187] op_sel_hi:[1,0]
	v_pk_add_f32 v[184:185], v[138:139], v[140:141]
	v_pk_add_f32 v[186:187], v[142:143], v[144:145]
	v_pk_add_f32 v[184:185], v[184:185], v[146:147]
	v_pk_add_f32 v[186:187], v[186:187], v[148:149]
	v_pk_add_f32 v[184:185], v[184:185], v[150:151]
	v_pk_add_f32 v[186:187], v[186:187], v[152:153]
	v_pk_add_f32 v[184:185], v[184:185], v[186:187]
	v_add_f32_e32 v183, v184, v185
	v_add_f32_e32 v198, v198, v183
	v_cvt_pk_bf16_f32 v138, v138, v139
	v_cvt_pk_bf16_f32 v139, v140, v141
	v_cvt_pk_bf16_f32 v140, v142, v143
	v_cvt_pk_bf16_f32 v141, v144, v145
	v_cvt_pk_bf16_f32 v142, v146, v147
	v_cvt_pk_bf16_f32 v143, v148, v149
	v_cvt_pk_bf16_f32 v144, v150, v151
	v_cvt_pk_bf16_f32 v145, v152, v153
	v_max3_f32 v183, v154, v155, v156
	v_max3_f32 v184, v157, v158, v159
	v_max3_f32 v185, v160, v161, v162
	s_waitcnt vmcnt(5)
	v_mfma_f32_32x32x16_bf16 v[74:89], v[22:25], v[138:141], v[74:89]
	v_max3_f32 v186, v163, v164, v165
	v_max3_f32 v187, v166, v167, v168
	v_max3_f32 v183, v183, v184, v185
	v_mfma_f32_32x32x16_bf16 v[90:105], v[30:33], v[138:141], v[90:105]
	v_max3_f32 v186, v186, v187, v169
	v_max_f32_e32 v183, v183, v186
	v_mov_b32_e32 v184, v183
	s_nop 1
	v_permlane32_swap_b32_e32 v184, v183
	v_max_f32_e32 v183, v183, v184
	v_fma_f32 v183, v183, s14, v203
	v_max_f32_e32 v184, v201, v183
	v_sub_f32_e32 v186, v201, v184
	v_exp_f32_e32 v186, v186
	v_mov_b32_e32 v201, v184
	v_sub_f32_e32 v204, v203, v184
	v_pk_fma_f32 v[154:155], v[154:155], v[192:193], v[204:205] op_sel_hi:[1,0,0]
	v_exp_f32_e32 v154, v154
	v_exp_f32_e32 v155, v155
	v_pk_fma_f32 v[156:157], v[156:157], v[192:193], v[204:205] op_sel_hi:[1,0,0]
	v_exp_f32_e32 v156, v156
	v_exp_f32_e32 v157, v157
	v_pk_fma_f32 v[158:159], v[158:159], v[192:193], v[204:205] op_sel_hi:[1,0,0]
	v_exp_f32_e32 v158, v158
	v_exp_f32_e32 v159, v159
	v_pk_fma_f32 v[160:161], v[160:161], v[192:193], v[204:205] op_sel_hi:[1,0,0]
	v_exp_f32_e32 v160, v160
	v_exp_f32_e32 v161, v161
	v_mfma_f32_32x32x16_bf16 v[74:89], v[26:29], v[142:145], v[74:89]
	v_pk_fma_f32 v[162:163], v[162:163], v[192:193], v[204:205] op_sel_hi:[1,0,0]
	v_exp_f32_e32 v162, v162
	v_exp_f32_e32 v163, v163
	v_pk_fma_f32 v[164:165], v[164:165], v[192:193], v[204:205] op_sel_hi:[1,0,0]
	v_mfma_f32_32x32x16_bf16 v[90:105], v[34:37], v[142:145], v[90:105]
	v_exp_f32_e32 v164, v164
	v_exp_f32_e32 v165, v165
	v_pk_fma_f32 v[166:167], v[166:167], v[192:193], v[204:205] op_sel_hi:[1,0,0]
	v_exp_f32_e32 v166, v166
	v_exp_f32_e32 v167, v167
	v_pk_fma_f32 v[168:169], v[168:169], v[192:193], v[204:205] op_sel_hi:[1,0,0]
	v_exp_f32_e32 v168, v168
	v_exp_f32_e32 v169, v169
	v_mul_f32_e32 v202, v202, v186
	v_pk_mul_f32 v[106:107], v[106:107], v[186:187] op_sel_hi:[1,0]
	v_pk_mul_f32 v[108:109], v[108:109], v[186:187] op_sel_hi:[1,0]
	v_pk_mul_f32 v[110:111], v[110:111], v[186:187] op_sel_hi:[1,0]
	v_pk_mul_f32 v[112:113], v[112:113], v[186:187] op_sel_hi:[1,0]
	v_pk_mul_f32 v[114:115], v[114:115], v[186:187] op_sel_hi:[1,0]
	v_pk_mul_f32 v[116:117], v[116:117], v[186:187] op_sel_hi:[1,0]
	v_pk_mul_f32 v[118:119], v[118:119], v[186:187] op_sel_hi:[1,0]
	v_pk_mul_f32 v[120:121], v[120:121], v[186:187] op_sel_hi:[1,0]
	v_pk_mul_f32 v[122:123], v[122:123], v[186:187] op_sel_hi:[1,0]
	v_pk_mul_f32 v[124:125], v[124:125], v[186:187] op_sel_hi:[1,0]
	v_pk_mul_f32 v[126:127], v[126:127], v[186:187] op_sel_hi:[1,0]
	v_pk_mul_f32 v[128:129], v[128:129], v[186:187] op_sel_hi:[1,0]
	v_pk_mul_f32 v[130:131], v[130:131], v[186:187] op_sel_hi:[1,0]
	v_pk_mul_f32 v[132:133], v[132:133], v[186:187] op_sel_hi:[1,0]
	v_pk_mul_f32 v[134:135], v[134:135], v[186:187] op_sel_hi:[1,0]
	v_pk_mul_f32 v[136:137], v[136:137], v[186:187] op_sel_hi:[1,0]
	v_pk_add_f32 v[184:185], v[154:155], v[156:157]
	v_pk_add_f32 v[186:187], v[158:159], v[160:161]
	v_pk_add_f32 v[184:185], v[184:185], v[162:163]
	v_pk_add_f32 v[186:187], v[186:187], v[164:165]
	v_pk_add_f32 v[184:185], v[184:185], v[166:167]
	v_pk_add_f32 v[186:187], v[186:187], v[168:169]
	v_pk_add_f32 v[184:185], v[184:185], v[186:187]
	v_add_f32_e32 v183, v184, v185
	v_add_f32_e32 v202, v202, v183
	v_cvt_pk_bf16_f32 v154, v154, v155
	v_cvt_pk_bf16_f32 v155, v156, v157
	v_cvt_pk_bf16_f32 v156, v158, v159
	v_cvt_pk_bf16_f32 v157, v160, v161
	v_cvt_pk_bf16_f32 v158, v162, v163
	v_cvt_pk_bf16_f32 v159, v164, v165
	v_cvt_pk_bf16_f32 v160, v166, v167
	v_cvt_pk_bf16_f32 v161, v168, v169
	s_nop 1
	v_mfma_f32_32x32x16_bf16 v[106:121], v[22:25], v[154:157], v[106:121]
	v_mfma_f32_32x32x16_bf16 v[122:137], v[30:33], v[154:157], v[122:137]
	v_mfma_f32_32x32x16_bf16 v[106:121], v[26:29], v[158:161], v[106:121]
	v_mfma_f32_32x32x16_bf16 v[122:137], v[34:37], v[158:161], v[122:137]
	s_lshl_b32 s17, s18, 12
	v_add_u32_e32 v208, s17, v194
	global_load_dwordx4 v[22:25], v208, s[6:7]
	global_load_dwordx4 v[26:29], v208, s[6:7] offset:1024
	global_load_dwordx4 v[30:33], v208, s[6:7] offset:2048
	global_load_dwordx4 v[34:37], v208, s[6:7] offset:3072
	s_add_i32 s16, s16, 1
	s_cmp_lt_u32 s16, s15
	s_cbranch_scc1 .Lfox_loop
.Lfox_tail:
	s_waitcnt vmcnt(4)
	v_mfma_f32_32x32x16_bf16 v[138:153], v[2:5], v[38:41], 0
	v_mfma_f32_32x32x16_bf16 v[138:153], v[6:9], v[42:45], v[138:153]
	v_mfma_f32_32x32x16_bf16 v[138:153], v[10:13], v[46:49], v[138:153]
	v_mfma_f32_32x32x16_bf16 v[138:153], v[14:17], v[50:53], v[138:153]
	v_mfma_f32_32x32x16_bf16 v[138:153], v[18:21], v[70:73], v[138:153]
	v_mfma_f32_32x32x16_bf16 v[154:169], v[2:5], v[54:57], 0
	s_nop 7
	s_nop 4
	v_cmp_le_i32_e64 s[34:35], 0, v170
	v_cmp_le_i32_e64 s[36:37], 1, v170
	v_cmp_le_i32_e64 s[38:39], 2, v170
	v_cmp_le_i32_e64 s[40:41], 3, v170
	v_cmp_le_i32_e32 vcc, 8, v170
	v_cndmask_b32_e64 v138, v193, v138, s[34:35]
	v_cndmask_b32_e64 v139, v193, v139, s[36:37]
	v_cndmask_b32_e64 v140, v193, v140, s[38:39]
	v_cndmask_b32_e64 v141, v193, v141, s[40:41]
	v_cndmask_b32_e64 v142, v193, v142, vcc
	v_cmp_le_i32_e64 s[34:35], 9, v170
	v_cmp_le_i32_e64 s[36:37], 10, v170
	v_cmp_le_i32_e64 s[38:39], 11, v170
	v_cmp_le_i32_e64 s[40:41], 16, v170
	v_cmp_le_i32_e32 vcc, 17, v170
	v_cndmask_b32_e64 v143, v193, v143, s[34:35]
	v_cndmask_b32_e64 v144, v193, v144, s[36:37]
	v_cndmask_b32_e64 v145, v193, v145, s[38:39]
	v_cndmask_b32_e64 v146, v193, v146, s[40:41]
	v_cndmask_b32_e64 v147, v193, v147, vcc
	v_cmp_le_i32_e64 s[34:35], 18, v170
	v_cmp_le_i32_e64 s[36:37], 19, v170
	v_cmp_le_i32_e64 s[38:39], 24, v170
	v_cmp_le_i32_e64 s[40:41], 25, v170
	v_cmp_le_i32_e32 vcc, 26, v170
	v_cndmask_b32_e64 v148, v193, v148, s[34:35]
	v_cndmask_b32_e64 v149, v193, v149, s[36:37]
	v_cndmask_b32_e64 v150, v193, v150, s[38:39]
	v_cndmask_b32_e64 v151, v193, v151, s[40:41]
	v_cndmask_b32_e64 v152, v193, v152, vcc
	v_cmp_le_i32_e64 s[34:35], 27, v170
	s_nop 1
	v_cndmask_b32_e64 v153, v193, v153, s[34:35]
	v_max3_f32 v183, v138, v139, v140
	v_max3_f32 v184, v141, v142, v143
	v_max3_f32 v185, v144, v145, v146
	v_max3_f32 v186, v147, v148, v149
	v_max3_f32 v187, v150, v151, v152
	v_max3_f32 v183, v183, v184, v185
	v_max3_f32 v186, v186, v187, v153
	v_max_f32_e32 v183, v183, v186
	v_mov_b32_e32 v184, v183
	s_nop 1
	v_permlane32_swap_b32_e32 v184, v183
	v_max_f32_e32 v183, v183, v184
	v_fma_f32 v183, v183, s14, v199
	v_max_f32_e32 v184, v197, v183
	v_mfma_f32_32x32x16_bf16 v[154:169], v[6:9], v[58:61], v[154:169]
	v_sub_f32_e32 v186, v197, v184
	v_exp_f32_e32 v186, v186
	v_mov_b32_e32 v197, v184
	v_sub_f32_e32 v200, v199, v184
	v_pk_fma_f32 v[138:139], v[138:139], v[192:193], v[200:201] op_sel_hi:[1,0,0]
	v_exp_f32_e32 v138, v138
	v_exp_f32_e32 v139, v139
	v_pk_fma_f32 v[140:141], v[140:141], v[192:193], v[200:201] op_sel_hi:[1,0,0]
	v_exp_f32_e32 v140, v140
	v_exp_f32_e32 v141, v141
	v_pk_fma_f32 v[142:143], v[142:143], v[192:193], v[200:201] op_sel_hi:[1,0,0]
	v_exp_f32_e32 v142, v142
	v_exp_f32_e32 v143, v143
	v_pk_fma_f32 v[144:145], v[144:145], v[192:193], v[200:201] op_sel_hi:[1,0,0]
	v_mfma_f32_32x32x16_bf16 v[154:169], v[10:13], v[62:65], v[154:169]
	v_exp_f32_e32 v144, v144
	v_exp_f32_e32 v145, v145
	v_pk_fma_f32 v[146:147], v[146:147], v[192:193], v[200:201] op_sel_hi:[1,0,0]
	v_exp_f32_e32 v146, v146
	v_exp_f32_e32 v147, v147
	v_pk_fma_f32 v[148:149], v[148:149], v[192:193], v[200:201] op_sel_hi:[1,0,0]
	v_exp_f32_e32 v148, v148
	v_exp_f32_e32 v149, v149
	v_pk_fma_f32 v[150:151], v[150:151], v[192:193], v[200:201] op_sel_hi:[1,0,0]
	v_exp_f32_e32 v150, v150
	v_exp_f32_e32 v151, v151
	v_pk_fma_f32 v[152:153], v[152:153], v[192:193], v[200:201] op_sel_hi:[1,0,0]
	v_exp_f32_e32 v152, v152
	v_exp_f32_e32 v153, v153
	v_mfma_f32_32x32x16_bf16 v[154:169], v[14:17], v[66:69], v[154:169]
	v_mul_f32_e32 v198, v198, v186
	v_pk_mul_f32 v[74:75], v[74:75], v[186:187] op_sel_hi:[1,0]
	v_pk_mul_f32 v[76:77], v[76:77], v[186:187] op_sel_hi:[1,0]
	v_pk_mul_f32 v[78:79], v[78:79], v[186:187] op_sel_hi:[1,0]
	v_pk_mul_f32 v[80:81], v[80:81], v[186:187] op_sel_hi:[1,0]
	v_pk_mul_f32 v[82:83], v[82:83], v[186:187] op_sel_hi:[1,0]
	v_pk_mul_f32 v[84:85], v[84:85], v[186:187] op_sel_hi:[1,0]
	v_pk_mul_f32 v[86:87], v[86:87], v[186:187] op_sel_hi:[1,0]
	v_pk_mul_f32 v[88:89], v[88:89], v[186:187] op_sel_hi:[1,0]
	v_pk_mul_f32 v[90:91], v[90:91], v[186:187] op_sel_hi:[1,0]
	v_pk_mul_f32 v[92:93], v[92:93], v[186:187] op_sel_hi:[1,0]
	v_pk_mul_f32 v[94:95], v[94:95], v[186:187] op_sel_hi:[1,0]
	v_pk_mul_f32 v[96:97], v[96:97], v[186:187] op_sel_hi:[1,0]
	v_pk_mul_f32 v[98:99], v[98:99], v[186:187] op_sel_hi:[1,0]
	v_mfma_f32_32x32x16_bf16 v[154:169], v[18:21], v[70:73], v[154:169]
	s_add_i32 s18, s16, 1
	s_lshl_b32 s17, s18, 12
	v_add_u32_e32 v207, s17, v194
	global_load_dwordx4 v[2:5], v207, s[4:5]
	global_load_dwordx4 v[6:9], v207, s[4:5] offset:1024
	global_load_dwordx4 v[10:13], v207, s[4:5] offset:2048
	global_load_dwordx4 v[14:17], v207, s[4:5] offset:3072
	s_lshl_b32 s17, s18, 9
	v_add_u32_e32 v209, s17, v190
	s_mov_b64 exec, s[44:45]
	global_load_dwordx4 v[18:21], v209, s[8:9]
	s_mov_b64 exec, -1
	v_pk_mul_f32 v[100:101], v[100:101], v[186:187] op_sel_hi:[1,0]
	v_pk_mul_f32 v[102:103], v[102:103], v[186:187] op_sel_hi:[1,0]
	v_pk_mul_f32 v[104:105], v[104:105], v[186:187] op_sel_hi:[1,0]
	v_pk_add_f32 v[184:185], v[138:139], v[140:141]
	v_pk_add_f32 v[186:187], v[142:143], v[144:145]
	v_pk_add_f32 v[184:185], v[184:185], v[146:147]
	v_pk_add_f32 v[186:187], v[186:187], v[148:149]
	v_pk_add_f32 v[184:185], v[184:185], v[150:151]
	v_pk_add_f32 v[186:187], v[186:187], v[152:153]
	v_pk_add_f32 v[184:185], v[184:185], v[186:187]
	v_add_f32_e32 v183, v184, v185
	v_add_f32_e32 v198, v198, v183
	v_cvt_pk_bf16_f32 v138, v138, v139
	v_cvt_pk_bf16_f32 v139, v140, v141
	v_cvt_pk_bf16_f32 v140, v142, v143
	v_cvt_pk_bf16_f32 v141, v144, v145
	v_cvt_pk_bf16_f32 v142, v146, v147
	v_cvt_pk_bf16_f32 v143, v148, v149
	v_cvt_pk_bf16_f32 v144, v150, v151
	v_cvt_pk_bf16_f32 v145, v152, v153
	v_max3_f32 v183, v154, v155, v156
	v_max3_f32 v184, v157, v158, v159
	v_max3_f32 v185, v160, v161, v162
	s_waitcnt vmcnt(5)
	v_mfma_f32_32x32x16_bf16 v[74:89], v[22:25], v[138:141], v[74:89]
	v_max3_f32 v186, v163, v164, v165
	v_max3_f32 v187, v166, v167, v168
	v_max3_f32 v183, v183, v184, v185
	v_mfma_f32_32x32x16_bf16 v[90:105], v[30:33], v[138:141], v[90:105]
	v_max3_f32 v186, v186, v187, v169
	v_max_f32_e32 v183, v183, v186
	v_mov_b32_e32 v184, v183
	s_nop 1
	v_permlane32_swap_b32_e32 v184, v183
	v_max_f32_e32 v183, v183, v184
	v_fma_f32 v183, v183, s14, v203
	v_max_f32_e32 v184, v201, v183
	v_sub_f32_e32 v186, v201, v184
	v_exp_f32_e32 v186, v186
	v_mov_b32_e32 v201, v184
	v_sub_f32_e32 v204, v203, v184
	v_pk_fma_f32 v[154:155], v[154:155], v[192:193], v[204:205] op_sel_hi:[1,0,0]
	v_exp_f32_e32 v154, v154
	v_exp_f32_e32 v155, v155
	v_pk_fma_f32 v[156:157], v[156:157], v[192:193], v[204:205] op_sel_hi:[1,0,0]
	v_exp_f32_e32 v156, v156
	v_exp_f32_e32 v157, v157
	v_pk_fma_f32 v[158:159], v[158:159], v[192:193], v[204:205] op_sel_hi:[1,0,0]
	v_exp_f32_e32 v158, v158
	v_exp_f32_e32 v159, v159
	v_pk_fma_f32 v[160:161], v[160:161], v[192:193], v[204:205] op_sel_hi:[1,0,0]
	v_exp_f32_e32 v160, v160
	v_exp_f32_e32 v161, v161
	v_mfma_f32_32x32x16_bf16 v[74:89], v[26:29], v[142:145], v[74:89]
	v_pk_fma_f32 v[162:163], v[162:163], v[192:193], v[204:205] op_sel_hi:[1,0,0]
	v_exp_f32_e32 v162, v162
	v_exp_f32_e32 v163, v163
	v_pk_fma_f32 v[164:165], v[164:165], v[192:193], v[204:205] op_sel_hi:[1,0,0]
	v_mfma_f32_32x32x16_bf16 v[90:105], v[34:37], v[142:145], v[90:105]
	v_exp_f32_e32 v164, v164
	v_exp_f32_e32 v165, v165
	v_pk_fma_f32 v[166:167], v[166:167], v[192:193], v[204:205] op_sel_hi:[1,0,0]
	v_exp_f32_e32 v166, v166
	v_exp_f32_e32 v167, v167
	v_pk_fma_f32 v[168:169], v[168:169], v[192:193], v[204:205] op_sel_hi:[1,0,0]
	v_exp_f32_e32 v168, v168
	v_exp_f32_e32 v169, v169
	v_mul_f32_e32 v202, v202, v186
	v_pk_mul_f32 v[106:107], v[106:107], v[186:187] op_sel_hi:[1,0]
	v_pk_mul_f32 v[108:109], v[108:109], v[186:187] op_sel_hi:[1,0]
	v_pk_mul_f32 v[110:111], v[110:111], v[186:187] op_sel_hi:[1,0]
	v_pk_mul_f32 v[112:113], v[112:113], v[186:187] op_sel_hi:[1,0]
	v_pk_mul_f32 v[114:115], v[114:115], v[186:187] op_sel_hi:[1,0]
	v_pk_mul_f32 v[116:117], v[116:117], v[186:187] op_sel_hi:[1,0]
	v_pk_mul_f32 v[118:119], v[118:119], v[186:187] op_sel_hi:[1,0]
	v_pk_mul_f32 v[120:121], v[120:121], v[186:187] op_sel_hi:[1,0]
	v_pk_mul_f32 v[122:123], v[122:123], v[186:187] op_sel_hi:[1,0]
	v_pk_mul_f32 v[124:125], v[124:125], v[186:187] op_sel_hi:[1,0]
	v_pk_mul_f32 v[126:127], v[126:127], v[186:187] op_sel_hi:[1,0]
	v_pk_mul_f32 v[128:129], v[128:129], v[186:187] op_sel_hi:[1,0]
	v_pk_mul_f32 v[130:131], v[130:131], v[186:187] op_sel_hi:[1,0]
	v_pk_mul_f32 v[132:133], v[132:133], v[186:187] op_sel_hi:[1,0]
	v_pk_mul_f32 v[134:135], v[134:135], v[186:187] op_sel_hi:[1,0]
	v_pk_mul_f32 v[136:137], v[136:137], v[186:187] op_sel_hi:[1,0]
	v_pk_add_f32 v[184:185], v[154:155], v[156:157]
	v_pk_add_f32 v[186:187], v[158:159], v[160:161]
	v_pk_add_f32 v[184:185], v[184:185], v[162:163]
	v_pk_add_f32 v[186:187], v[186:187], v[164:165]
	v_pk_add_f32 v[184:185], v[184:185], v[166:167]
	v_pk_add_f32 v[186:187], v[186:187], v[168:169]
	v_pk_add_f32 v[184:185], v[184:185], v[186:187]
	v_add_f32_e32 v183, v184, v185
	v_add_f32_e32 v202, v202, v183
	v_cvt_pk_bf16_f32 v154, v154, v155
	v_cvt_pk_bf16_f32 v155, v156, v157
	v_cvt_pk_bf16_f32 v156, v158, v159
	v_cvt_pk_bf16_f32 v157, v160, v161
	v_cvt_pk_bf16_f32 v158, v162, v163
	v_cvt_pk_bf16_f32 v159, v164, v165
	v_cvt_pk_bf16_f32 v160, v166, v167
	v_cvt_pk_bf16_f32 v161, v168, v169
	s_nop 1
	v_mfma_f32_32x32x16_bf16 v[106:121], v[22:25], v[154:157], v[106:121]
	v_mfma_f32_32x32x16_bf16 v[122:137], v[30:33], v[154:157], v[122:137]
	v_mfma_f32_32x32x16_bf16 v[106:121], v[26:29], v[158:161], v[106:121]
	v_mfma_f32_32x32x16_bf16 v[122:137], v[34:37], v[158:161], v[122:137]
	s_lshl_b32 s17, s18, 12
	v_add_u32_e32 v208, s17, v194
	global_load_dwordx4 v[22:25], v208, s[6:7]
	global_load_dwordx4 v[26:29], v208, s[6:7] offset:1024
	global_load_dwordx4 v[30:33], v208, s[6:7] offset:2048
	global_load_dwordx4 v[34:37], v208, s[6:7] offset:3072
	s_add_i32 s16, s16, 1
	s_waitcnt vmcnt(4)
	v_mfma_f32_32x32x16_bf16 v[154:169], v[2:5], v[54:57], 0
	v_mfma_f32_32x32x16_bf16 v[154:169], v[6:9], v[58:61], v[154:169]
	v_mfma_f32_32x32x16_bf16 v[154:169], v[10:13], v[62:65], v[154:169]
	v_mfma_f32_32x32x16_bf16 v[154:169], v[14:17], v[66:69], v[154:169]
	v_mfma_f32_32x32x16_bf16 v[154:169], v[18:21], v[70:73], v[154:169]
	s_nop 7
	s_nop 4
	v_cmp_le_i32_e64 s[34:35], 0, v170
	v_cmp_le_i32_e64 s[36:37], 1, v170
	v_cmp_le_i32_e64 s[38:39], 2, v170
	v_cmp_le_i32_e64 s[40:41], 3, v170
	v_cmp_le_i32_e32 vcc, 8, v170
	v_cndmask_b32_e64 v154, v193, v154, s[34:35]
	v_cndmask_b32_e64 v155, v193, v155, s[36:37]
	v_cndmask_b32_e64 v156, v193, v156, s[38:39]
	v_cndmask_b32_e64 v157, v193, v157, s[40:41]
	v_cndmask_b32_e64 v158, v193, v158, vcc
	v_cmp_le_i32_e64 s[34:35], 9, v170
	v_cmp_le_i32_e64 s[36:37], 10, v170
	v_cmp_le_i32_e64 s[38:39], 11, v170
	v_cmp_le_i32_e64 s[40:41], 16, v170
	v_cmp_le_i32_e32 vcc, 17, v170
	v_cndmask_b32_e64 v159, v193, v159, s[34:35]
	v_cndmask_b32_e64 v160, v193, v160, s[36:37]
	v_cndmask_b32_e64 v161, v193, v161, s[38:39]
	v_cndmask_b32_e64 v162, v193, v162, s[40:41]
	v_cndmask_b32_e64 v163, v193, v163, vcc
	v_cmp_le_i32_e64 s[34:35], 18, v170
	v_cmp_le_i32_e64 s[36:37], 19, v170
	v_cmp_le_i32_e64 s[38:39], 24, v170
	v_cmp_le_i32_e64 s[40:41], 25, v170
	v_cmp_le_i32_e32 vcc, 26, v170
	v_cndmask_b32_e64 v164, v193, v164, s[34:35]
	v_cndmask_b32_e64 v165, v193, v165, s[36:37]
	v_cndmask_b32_e64 v166, v193, v166, s[38:39]
	v_cndmask_b32_e64 v167, v193, v167, s[40:41]
	v_cndmask_b32_e64 v168, v193, v168, vcc
	v_cmp_le_i32_e64 s[34:35], 27, v170
	s_nop 1
	v_cndmask_b32_e64 v169, v193, v169, s[34:35]
	v_max3_f32 v183, v154, v155, v156
	v_max3_f32 v184, v157, v158, v159
	v_max3_f32 v185, v160, v161, v162
	v_max3_f32 v186, v163, v164, v165
	v_max3_f32 v187, v166, v167, v168
	v_max3_f32 v183, v183, v184, v185
	v_max3_f32 v186, v186, v187, v169
	v_max_f32_e32 v183, v183, v186
	v_mov_b32_e32 v184, v183
	s_nop 1
	v_permlane32_swap_b32_e32 v184, v183
	s_waitcnt vmcnt(0)
	v_max_f32_e32 v183, v183, v184
	v_fma_f32 v183, v183, s14, v203
	v_max_f32_e32 v184, v201, v183
	v_sub_f32_e32 v186, v201, v184
	v_exp_f32_e32 v186, v186
	v_mov_b32_e32 v201, v184
	v_sub_f32_e32 v204, v203, v184
	v_pk_fma_f32 v[154:155], v[154:155], v[192:193], v[204:205] op_sel_hi:[1,0,0]
	v_exp_f32_e32 v154, v154
	v_exp_f32_e32 v155, v155
	v_pk_fma_f32 v[156:157], v[156:157], v[192:193], v[204:205] op_sel_hi:[1,0,0]
	v_exp_f32_e32 v156, v156
	v_exp_f32_e32 v157, v157
	v_pk_fma_f32 v[158:159], v[158:159], v[192:193], v[204:205] op_sel_hi:[1,0,0]
	v_exp_f32_e32 v158, v158
	v_exp_f32_e32 v159, v159
	v_pk_fma_f32 v[160:161], v[160:161], v[192:193], v[204:205] op_sel_hi:[1,0,0]
	v_exp_f32_e32 v160, v160
	v_exp_f32_e32 v161, v161
	v_pk_fma_f32 v[162:163], v[162:163], v[192:193], v[204:205] op_sel_hi:[1,0,0]
	v_exp_f32_e32 v162, v162
	v_exp_f32_e32 v163, v163
	v_pk_fma_f32 v[164:165], v[164:165], v[192:193], v[204:205] op_sel_hi:[1,0,0]
	v_exp_f32_e32 v164, v164
	v_exp_f32_e32 v165, v165
	v_pk_fma_f32 v[166:167], v[166:167], v[192:193], v[204:205] op_sel_hi:[1,0,0]
	v_exp_f32_e32 v166, v166
	v_exp_f32_e32 v167, v167
	v_pk_fma_f32 v[168:169], v[168:169], v[192:193], v[204:205] op_sel_hi:[1,0,0]
	v_exp_f32_e32 v168, v168
	v_exp_f32_e32 v169, v169
	v_mul_f32_e32 v202, v202, v186
	v_pk_mul_f32 v[106:107], v[106:107], v[186:187] op_sel_hi:[1,0]
	v_pk_mul_f32 v[108:109], v[108:109], v[186:187] op_sel_hi:[1,0]
	v_pk_mul_f32 v[110:111], v[110:111], v[186:187] op_sel_hi:[1,0]
	v_pk_mul_f32 v[112:113], v[112:113], v[186:187] op_sel_hi:[1,0]
	v_pk_mul_f32 v[114:115], v[114:115], v[186:187] op_sel_hi:[1,0]
	v_pk_mul_f32 v[116:117], v[116:117], v[186:187] op_sel_hi:[1,0]
	v_pk_mul_f32 v[118:119], v[118:119], v[186:187] op_sel_hi:[1,0]
	v_pk_mul_f32 v[120:121], v[120:121], v[186:187] op_sel_hi:[1,0]
	v_pk_mul_f32 v[122:123], v[122:123], v[186:187] op_sel_hi:[1,0]
	v_pk_mul_f32 v[124:125], v[124:125], v[186:187] op_sel_hi:[1,0]
	v_pk_mul_f32 v[126:127], v[126:127], v[186:187] op_sel_hi:[1,0]
	v_pk_mul_f32 v[128:129], v[128:129], v[186:187] op_sel_hi:[1,0]
	v_pk_mul_f32 v[130:131], v[130:131], v[186:187] op_sel_hi:[1,0]
	v_pk_mul_f32 v[132:133], v[132:133], v[186:187] op_sel_hi:[1,0]
	v_pk_mul_f32 v[134:135], v[134:135], v[186:187] op_sel_hi:[1,0]
	v_pk_mul_f32 v[136:137], v[136:137], v[186:187] op_sel_hi:[1,0]
	v_pk_add_f32 v[184:185], v[154:155], v[156:157]
	v_pk_add_f32 v[186:187], v[158:159], v[160:161]
	v_pk_add_f32 v[184:185], v[184:185], v[162:163]
	v_pk_add_f32 v[186:187], v[186:187], v[164:165]
	v_pk_add_f32 v[184:185], v[184:185], v[166:167]
	v_pk_add_f32 v[186:187], v[186:187], v[168:169]
	v_pk_add_f32 v[184:185], v[184:185], v[186:187]
	v_add_f32_e32 v183, v184, v185
	v_add_f32_e32 v202, v202, v183
	v_cvt_pk_bf16_f32 v154, v154, v155
	v_cvt_pk_bf16_f32 v155, v156, v157
	v_cvt_pk_bf16_f32 v156, v158, v159
	v_cvt_pk_bf16_f32 v157, v160, v161
	v_cvt_pk_bf16_f32 v158, v162, v163
	v_cvt_pk_bf16_f32 v159, v164, v165
	v_cvt_pk_bf16_f32 v160, v166, v167
	v_cvt_pk_bf16_f32 v161, v168, v169
	s_nop 1
	v_mfma_f32_32x32x16_bf16 v[106:121], v[22:25], v[154:157], v[106:121]
	v_mfma_f32_32x32x16_bf16 v[122:137], v[30:33], v[154:157], v[122:137]
	v_mfma_f32_32x32x16_bf16 v[106:121], v[26:29], v[158:161], v[106:121]
	v_mfma_f32_32x32x16_bf16 v[122:137], v[34:37], v[158:161], v[122:137]
	s_nop 7
	s_nop 7
	v_mov_b32_e32 v184, v198
	s_nop 1
	v_permlane32_swap_b32_e32 v184, v198
	v_add_f32_e32 v198, v198, v184
	v_rcp_f32_e32 v186, v198
	s_nop 0
	v_fma_f32 v184, -v198, v186, 1.0
	v_fma_f32 v186, v186, v184, v186
	v_pk_mul_f32 v[74:75], v[74:75], v[186:187] op_sel_hi:[1,0]
	v_pk_mul_f32 v[76:77], v[76:77], v[186:187] op_sel_hi:[1,0]
	v_pk_mul_f32 v[78:79], v[78:79], v[186:187] op_sel_hi:[1,0]
	v_pk_mul_f32 v[80:81], v[80:81], v[186:187] op_sel_hi:[1,0]
	v_pk_mul_f32 v[82:83], v[82:83], v[186:187] op_sel_hi:[1,0]
	v_pk_mul_f32 v[84:85], v[84:85], v[186:187] op_sel_hi:[1,0]
	v_pk_mul_f32 v[86:87], v[86:87], v[186:187] op_sel_hi:[1,0]
	v_pk_mul_f32 v[88:89], v[88:89], v[186:187] op_sel_hi:[1,0]
	v_pk_mul_f32 v[90:91], v[90:91], v[186:187] op_sel_hi:[1,0]
	v_pk_mul_f32 v[92:93], v[92:93], v[186:187] op_sel_hi:[1,0]
	v_pk_mul_f32 v[94:95], v[94:95], v[186:187] op_sel_hi:[1,0]
	v_pk_mul_f32 v[96:97], v[96:97], v[186:187] op_sel_hi:[1,0]
	v_pk_mul_f32 v[98:99], v[98:99], v[186:187] op_sel_hi:[1,0]
	v_pk_mul_f32 v[100:101], v[100:101], v[186:187] op_sel_hi:[1,0]
	v_pk_mul_f32 v[102:103], v[102:103], v[186:187] op_sel_hi:[1,0]
	v_pk_mul_f32 v[104:105], v[104:105], v[186:187] op_sel_hi:[1,0]
	v_cvt_pk_bf16_f32 v74, v74, v75
	v_cvt_pk_bf16_f32 v75, v76, v77
	global_store_dwordx2 v205, v[74:75], s[12:13]
	v_cvt_pk_bf16_f32 v78, v78, v79
	v_cvt_pk_bf16_f32 v79, v80, v81
	global_store_dwordx2 v205, v[78:79], s[12:13] offset:16
	v_cvt_pk_bf16_f32 v82, v82, v83
	v_cvt_pk_bf16_f32 v83, v84, v85
	global_store_dwordx2 v205, v[82:83], s[12:13] offset:32
	v_cvt_pk_bf16_f32 v86, v86, v87
	v_cvt_pk_bf16_f32 v87, v88, v89
	global_store_dwordx2 v205, v[86:87], s[12:13] offset:48
	v_cvt_pk_bf16_f32 v90, v90, v91
	v_cvt_pk_bf16_f32 v91, v92, v93
	global_store_dwordx2 v205, v[90:91], s[12:13] offset:64
	v_cvt_pk_bf16_f32 v94, v94, v95
	v_cvt_pk_bf16_f32 v95, v96, v97
	global_store_dwordx2 v205, v[94:95], s[12:13] offset:80
	v_cvt_pk_bf16_f32 v98, v98, v99
	v_cvt_pk_bf16_f32 v99, v100, v101
	global_store_dwordx2 v205, v[98:99], s[12:13] offset:96
	v_cvt_pk_bf16_f32 v102, v102, v103
	v_cvt_pk_bf16_f32 v103, v104, v105
	global_store_dwordx2 v205, v[102:103], s[12:13] offset:112
	v_mov_b32_e32 v184, v202
	s_nop 1
	v_permlane32_swap_b32_e32 v184, v202
	v_add_f32_e32 v202, v202, v184
	v_rcp_f32_e32 v186, v202
	s_nop 0
	v_fma_f32 v184, -v202, v186, 1.0
	v_fma_f32 v186, v186, v184, v186
	v_pk_mul_f32 v[106:107], v[106:107], v[186:187] op_sel_hi:[1,0]
	v_pk_mul_f32 v[108:109], v[108:109], v[186:187] op_sel_hi:[1,0]
	v_pk_mul_f32 v[110:111], v[110:111], v[186:187] op_sel_hi:[1,0]
	v_pk_mul_f32 v[112:113], v[112:113], v[186:187] op_sel_hi:[1,0]
	v_pk_mul_f32 v[114:115], v[114:115], v[186:187] op_sel_hi:[1,0]
	v_pk_mul_f32 v[116:117], v[116:117], v[186:187] op_sel_hi:[1,0]
	v_pk_mul_f32 v[118:119], v[118:119], v[186:187] op_sel_hi:[1,0]
	v_pk_mul_f32 v[120:121], v[120:121], v[186:187] op_sel_hi:[1,0]
	v_pk_mul_f32 v[122:123], v[122:123], v[186:187] op_sel_hi:[1,0]
	v_pk_mul_f32 v[124:125], v[124:125], v[186:187] op_sel_hi:[1,0]
	v_pk_mul_f32 v[126:127], v[126:127], v[186:187] op_sel_hi:[1,0]
	v_pk_mul_f32 v[128:129], v[128:129], v[186:187] op_sel_hi:[1,0]
	v_pk_mul_f32 v[130:131], v[130:131], v[186:187] op_sel_hi:[1,0]
	v_pk_mul_f32 v[132:133], v[132:133], v[186:187] op_sel_hi:[1,0]
	v_pk_mul_f32 v[134:135], v[134:135], v[186:187] op_sel_hi:[1,0]
	v_pk_mul_f32 v[136:137], v[136:137], v[186:187] op_sel_hi:[1,0]
	v_cvt_pk_bf16_f32 v106, v106, v107
	v_cvt_pk_bf16_f32 v107, v108, v109
	global_store_dwordx2 v206, v[106:107], s[12:13]
	v_cvt_pk_bf16_f32 v110, v110, v111
	v_cvt_pk_bf16_f32 v111, v112, v113
	global_store_dwordx2 v206, v[110:111], s[12:13] offset:16
	v_cvt_pk_bf16_f32 v114, v114, v115
	v_cvt_pk_bf16_f32 v115, v116, v117
	global_store_dwordx2 v206, v[114:115], s[12:13] offset:32
	v_cvt_pk_bf16_f32 v118, v118, v119
	v_cvt_pk_bf16_f32 v119, v120, v121
	global_store_dwordx2 v206, v[118:119], s[12:13] offset:48
	v_cvt_pk_bf16_f32 v122, v122, v123
	v_cvt_pk_bf16_f32 v123, v124, v125
	global_store_dwordx2 v206, v[122:123], s[12:13] offset:64
	v_cvt_pk_bf16_f32 v126, v126, v127
	v_cvt_pk_bf16_f32 v127, v128, v129
	global_store_dwordx2 v206, v[126:127], s[12:13] offset:80
	v_cvt_pk_bf16_f32 v130, v130, v131
	v_cvt_pk_bf16_f32 v131, v132, v133
	global_store_dwordx2 v206, v[130:131], s[12:13] offset:96
	v_cvt_pk_bf16_f32 v134, v134, v135
	v_cvt_pk_bf16_f32 v135, v136, v137
	global_store_dwordx2 v206, v[134:135], s[12:13] offset:112
	s_waitcnt vmcnt(0)
	s_add_i32 s22, s22, s68
	s_cmpk_lt_i32 s22, 0x800
	s_cbranch_scc1 .Lfox_outer
	v_lshlrev_b32_e32 v2, 2, v220
	v_add_u32_e32 v3, 0x10000, v2
	ds_read_b32 v146, v2 offset:0
	ds_read_b32 v147, v2 offset:2048
	ds_read_b32 v148, v2 offset:4096
	ds_read_b32 v149, v2 offset:6144
	ds_read_b32 v150, v2 offset:8192
	ds_read_b32 v151, v2 offset:10240
	ds_read_b32 v152, v2 offset:12288
	ds_read_b32 v153, v2 offset:14336
	ds_read_b32 v154, v2 offset:16384
	ds_read_b32 v155, v2 offset:18432
	ds_read_b32 v156, v2 offset:20480
	ds_read_b32 v157, v2 offset:22528
	ds_read_b32 v158, v2 offset:24576
	ds_read_b32 v159, v2 offset:26624
	ds_read_b32 v160, v2 offset:28672
	ds_read_b32 v161, v2 offset:30720
	ds_read_b32 v162, v2 offset:32768
	ds_read_b32 v163, v2 offset:34816
	ds_read_b32 v164, v2 offset:36864
	ds_read_b32 v165, v2 offset:38912
	ds_read_b32 v166, v2 offset:40960
	ds_read_b32 v167, v2 offset:43008
	ds_read_b32 v168, v2 offset:45056
	ds_read_b32 v169, v2 offset:47104
	ds_read_b32 v170, v2 offset:49152
	ds_read_b32 v183, v2 offset:51200
	ds_read_b32 v184, v2 offset:53248
	ds_read_b32 v185, v2 offset:55296
	ds_read_b32 v186, v2 offset:57344
	ds_read_b32 v187, v2 offset:59392
	ds_read_b32 v188, v2 offset:61440
	ds_read_b32 v189, v2 offset:63488
	ds_read_b32 v190, v3 offset:0
	ds_read_b32 v191, v3 offset:2048
	ds_read_b32 v192, v3 offset:4096
	ds_read_b32 v193, v3 offset:6144
	ds_read_b32 v194, v3 offset:8192
	ds_read_b32 v195, v3 offset:10240
	ds_read_b32 v196, v3 offset:12288
	ds_read_b32 v197, v3 offset:14336
	ds_read_b32 v198, v3 offset:16384
	ds_read_b32 v199, v3 offset:18432
	ds_read_b32 v200, v3 offset:20480
	ds_read_b32 v201, v3 offset:22528
	ds_read_b32 v202, v3 offset:24576
	ds_read_b32 v203, v3 offset:26624
	ds_read_b32 v204, v3 offset:28672
	ds_read_b32 v205, v3 offset:30720
	ds_read_b32 v206, v3 offset:32768
	ds_read_b32 v207, v3 offset:34816
	ds_read_b32 v208, v3 offset:36864
	ds_read_b32 v209, v3 offset:38912
	ds_read_b32 v210, v3 offset:40960
	ds_read_b32 v211, v3 offset:43008
	ds_read_b32 v212, v3 offset:45056
	ds_read_b32 v213, v3 offset:47104
	ds_read_b32 v214, v3 offset:49152
	ds_read_b32 v215, v3 offset:51200
	ds_read_b32 v216, v3 offset:53248
	v_lshrrev_b32_e32 v2, 6, v220
	v_lshlrev_b32_e32 v2, 8, v2
	v_add_u32_e32 v2, 0x1d800, v2
	ds_read_b32 v4, v2 offset:0
	ds_read_b32 v5, v2 offset:4
	ds_read_b32 v6, v2 offset:8
	ds_read_b32 v7, v2 offset:12
	ds_read_b32 v8, v2 offset:16
	ds_read_b32 v9, v2 offset:20
	ds_read_b32 v10, v2 offset:24
	ds_read_b32 v11, v2 offset:28
	ds_read_b32 v12, v2 offset:32
	ds_read_b32 v13, v2 offset:36
	ds_read_b32 v14, v2 offset:40
	ds_read_b32 v15, v2 offset:44
	ds_read_b32 v16, v2 offset:48
	ds_read_b32 v17, v2 offset:52
	ds_read_b32 v18, v2 offset:56
	ds_read_b32 v19, v2 offset:60
	ds_read_b32 v20, v2 offset:64
	ds_read_b32 v21, v2 offset:68
	ds_read_b32 v22, v2 offset:72
	ds_read_b32 v23, v2 offset:76
	ds_read_b32 v24, v2 offset:80
	ds_read_b32 v25, v2 offset:84
	ds_read_b32 v26, v2 offset:88
	ds_read_b32 v27, v2 offset:92
	ds_read_b32 v28, v2 offset:96
	ds_read_b32 v29, v2 offset:100
	ds_read_b32 v30, v2 offset:104
	ds_read_b32 v31, v2 offset:108
	ds_read_b32 v32, v2 offset:112
	ds_read_b32 v33, v2 offset:116
	ds_read_b32 v34, v2 offset:120
	ds_read_b32 v35, v2 offset:124
	ds_read_b32 v36, v2 offset:128
	ds_read_b32 v37, v2 offset:132
	ds_read_b32 v38, v2 offset:136
	ds_read_b32 v39, v2 offset:140
	ds_read_b32 v40, v2 offset:144
	ds_read_b32 v41, v2 offset:148
	ds_read_b32 v42, v2 offset:152
	ds_read_b32 v43, v2 offset:156
	ds_read_b32 v44, v2 offset:160
	ds_read_b32 v45, v2 offset:164
	s_waitcnt lgkmcnt(0)
	v_readfirstlane_b32 s2, v4
	v_readfirstlane_b32 s3, v5
	v_readfirstlane_b32 s4, v6
	v_readfirstlane_b32 s5, v7
	v_readfirstlane_b32 s6, v8
	v_readfirstlane_b32 s7, v9
	v_readfirstlane_b32 s8, v10
	v_readfirstlane_b32 s9, v11
	v_readfirstlane_b32 s10, v12
	v_readfirstlane_b32 s11, v13
	v_readfirstlane_b32 s12, v14
	v_readfirstlane_b32 s13, v15
	v_readfirstlane_b32 s14, v16
	v_readfirstlane_b32 s15, v17
	v_readfirstlane_b32 s16, v18
	v_readfirstlane_b32 s17, v19
	v_readfirstlane_b32 s18, v20
	v_readfirstlane_b32 s19, v21
	v_readfirstlane_b32 s20, v22
	v_readfirstlane_b32 s21, v23
	v_readfirstlane_b32 s22, v24
	v_readfirstlane_b32 s23, v25
	v_readfirstlane_b32 s24, v26
	v_readfirstlane_b32 s25, v27
	v_readfirstlane_b32 s26, v28
	v_readfirstlane_b32 s27, v29
	v_readfirstlane_b32 s28, v30
	v_readfirstlane_b32 s29, v31
	v_readfirstlane_b32 s30, v32
	v_readfirstlane_b32 s31, v33
	v_readfirstlane_b32 s34, v34
	v_readfirstlane_b32 s35, v35
	v_readfirstlane_b32 s36, v36
	v_readfirstlane_b32 s37, v37
	v_readfirstlane_b32 s38, v38
	v_readfirstlane_b32 s39, v39
	v_readfirstlane_b32 s40, v40
	v_readfirstlane_b32 s41, v41
	v_readfirstlane_b32 s42, v42
	v_readfirstlane_b32 s43, v43
	v_readfirstlane_b32 s44, v44
	v_readfirstlane_b32 s45, v45
